# attention prologue loads+atomic merged; rowpass gain LDS reads hoisted (on v9)
# baseline (speedup 1.0000x reference)
; DI void rowpass(const Params& p, int l, bool first, int wv, char* smem) {
;     ...
;       for (int i = 0; i < 8; ++i) ss += yv[i][0] * yv[i][0] + yv[i][1] * yv[i][1] + yv[i][2] * yv[i][2] + yv[i][3] * yv[i][3];
;       const float* gate = p.mod + (size_t)(l * 5 + mr) * 6144 + 4096;
;       f32x4 gtv[8];
; #pragma unroll
;       for (int i = 0; i < 8; ++i) gtv[i] = *(const f32x4*)(gate + i * 256 + lane * 4);
;       f32x4 shv[8], scv[8];
;       if (l < 3) {
;         const float* shift = p.mod + (size_t)(lnext * 5 + mr) * 6144;
; #pragma unroll
;         for (int i = 0; i < 8; ++i) { shv[i] = *(const f32x4*)(shift + i * 256 + lane * 4); scv[i] = *(const f32x4*)(shift + 2048 + i * 256 + lane * 4); }
;       }
;       ss = wave_sum(ss);
;       const float r1 = rsqrtf(ss * (1.f / DM) + EPSV);
; #pragma unroll
;       for (int i = 0; i < 8; ++i) {
;         const f32x4 gpv = *(const f32x4*)(lg_post + i * 256 + lane * 4);
; #pragma unroll
;         for (int e = 0; e < 4; ++e) hv[i][e] += gtv[i][e] * ((yv[i][e] * r1) * gpv[e]);
;         *(f32x4*)(hout + i * 256 + lane * 4) = hv[i];
;       }
.LBB0_115:
	ds_read_b128 v[180:183], v212
	ds_read_b128 v[184:187], v212 offset:1024
	ds_read_b128 v[188:191], v212 offset:2048
	ds_read_b128 v[192:195], v212 offset:3072
	ds_read_b128 v[196:199], v212 offset:4096
	ds_read_b128 v[200:203], v212 offset:5120
	ds_read_b128 v[204:207], v212 offset:6144
	ds_read_b128 v[208:211], v212 offset:7168
	v_mul_f32_e32 v0, v139, v139
	v_mul_f32_e32 v164, v143, v143
	v_fmac_f32_e32 v164, v142, v142
	v_mul_f32_e32 v165, v147, v147
	v_fmac_f32_e32 v0, v138, v138
	v_fmac_f32_e32 v164, v144, v144
	v_fmac_f32_e32 v165, v146, v146
	v_mul_f32_e32 v172, v151, v151
	v_fmac_f32_e32 v0, v140, v140
	v_fmac_f32_e32 v164, v145, v145
	v_fmac_f32_e32 v165, v148, v148
	v_fmac_f32_e32 v172, v150, v150
	v_mul_f32_e32 v173, v167, v167
	v_fmac_f32_e32 v0, v141, v141
	v_fmac_f32_e32 v165, v149, v149
	v_fmac_f32_e32 v172, v152, v152
	v_fmac_f32_e32 v173, v166, v166
	v_mul_f32_e32 v174, v171, v171
	v_add_f32_e32 v0, v0, v164
	v_fmac_f32_e32 v172, v153, v153
	v_fmac_f32_e32 v173, v168, v168
	v_fmac_f32_e32 v174, v170, v170
	v_mul_f32_e32 v175, v157, v157
	v_add_f32_e32 v0, v165, v0
	v_fmac_f32_e32 v173, v169, v169
	v_fmac_f32_e32 v174, v154, v154
	v_fmac_f32_e32 v175, v156, v156
	v_mul_f32_e32 v176, v161, v161
	v_add_f32_e32 v0, v172, v0
	v_fmac_f32_e32 v174, v155, v155
	v_fmac_f32_e32 v175, v158, v158
	v_fmac_f32_e32 v176, v160, v160
	v_add_f32_e32 v0, v173, v0
	v_fmac_f32_e32 v175, v159, v159
	v_fmac_f32_e32 v176, v162, v162
	v_add_f32_e32 v0, v174, v0
	v_fmac_f32_e32 v176, v163, v163
	v_add_f32_e32 v0, v175, v0
	v_add_f32_e32 v0, v176, v0
	v_mov_b32_e32 v164, v0
	s_nop 1
	v_permlane32_swap_b32_e32 v0, v164
	v_add_f32_e32 v0, v0, v164
	ds_swizzle_b32 v164, v0 offset:swizzle(SWAP,16)
	s_mov_b32 s2, 0x800000
	s_waitcnt lgkmcnt(1)
	v_mov_b64_e32 v[172:173], v[180:181]
	v_mov_b64_e32 v[174:175], v[182:183]
	s_waitcnt lgkmcnt(0)
	v_add_f32_e32 v0, v0, v164
	ds_swizzle_b32 v164, v0 offset:swizzle(SWAP,8)
	s_waitcnt lgkmcnt(0)
	v_add_f32_e32 v0, v0, v164
	ds_swizzle_b32 v164, v0 offset:swizzle(SWAP,4)
	s_waitcnt lgkmcnt(0)
	v_add_f32_e32 v0, v0, v164
	ds_swizzle_b32 v164, v0 offset:swizzle(SWAP,2)
	s_waitcnt lgkmcnt(0)
	v_add_f32_e32 v0, v0, v164
	ds_swizzle_b32 v164, v0 offset:swizzle(SWAP,1)
	s_waitcnt lgkmcnt(0)
	v_add_f32_e32 v0, v0, v164
	v_fmamk_f32 v0, v0, 0x3a000000, v232
	v_cmp_gt_f32_e32 vcc, s2, v0
	v_mul_f32_e32 v164, 0x4b800000, v0
	s_nop 0
	v_cndmask_b32_e32 v0, v0, v164, vcc
	v_rsq_f32_e32 v0, v0
	s_nop 0
	v_mul_f32_e32 v164, 0x45800000, v0
	v_cndmask_b32_e32 v0, v0, v164, vcc
	v_pk_mul_f32 v[138:139], v[138:139], v[0:1] op_sel_hi:[1,0]
	v_lshl_add_u64 v[164:165], v[130:131], 2, s[0:1]
	v_pk_mul_f32 v[138:139], v[172:173], v[138:139]
	s_movk_i32 s0, 0x1000
	s_waitcnt vmcnt(5)
	v_pk_fma_f32 v[94:95], v[126:127], v[138:139], v[94:95]
	v_pk_mul_f32 v[126:127], v[140:141], v[0:1] op_sel_hi:[1,0]
	v_pk_mul_f32 v[138:139], v[142:143], v[0:1] op_sel_hi:[1,0]
	v_pk_mul_f32 v[126:127], v[174:175], v[126:127]
	s_nop 0
	v_pk_fma_f32 v[96:97], v[128:129], v[126:127], v[96:97]
	v_mov_b64_e32 v[126:127], v[184:185]
	v_mov_b64_e32 v[128:129], v[186:187]
	global_store_dwordx4 v[164:165], v[94:97], off
	s_waitcnt lgkmcnt(0)
	v_pk_mul_f32 v[126:127], v[126:127], v[138:139]
	s_nop 0
	v_pk_fma_f32 v[90:91], v[122:123], v[126:127], v[90:91]
	v_pk_mul_f32 v[122:123], v[144:145], v[0:1] op_sel_hi:[1,0]
	v_pk_mul_f32 v[126:127], v[146:147], v[0:1] op_sel_hi:[1,0]
	v_pk_mul_f32 v[122:123], v[128:129], v[122:123]
	s_nop 0
	v_pk_fma_f32 v[92:93], v[124:125], v[122:123], v[92:93]
	v_mov_b64_e32 v[122:123], v[188:189]
	v_mov_b64_e32 v[124:125], v[190:191]
	global_store_dwordx4 v[164:165], v[90:93], off offset:1024
	s_waitcnt lgkmcnt(0)
	v_pk_mul_f32 v[122:123], v[122:123], v[126:127]
	s_nop 0
	v_pk_fma_f32 v[86:87], v[118:119], v[122:123], v[86:87]
	v_pk_mul_f32 v[118:119], v[148:149], v[0:1] op_sel_hi:[1,0]
	v_pk_mul_f32 v[122:123], v[150:151], v[0:1] op_sel_hi:[1,0]
	v_pk_mul_f32 v[118:119], v[124:125], v[118:119]
	s_nop 0
	v_pk_fma_f32 v[88:89], v[120:121], v[118:119], v[88:89]
	v_mov_b64_e32 v[118:119], v[192:193]
	v_mov_b64_e32 v[120:121], v[194:195]
	global_store_dwordx4 v[164:165], v[86:89], off offset:2048
	s_waitcnt lgkmcnt(0)
	v_pk_mul_f32 v[118:119], v[118:119], v[122:123]
	s_waitcnt vmcnt(7)
	v_pk_fma_f32 v[82:83], v[114:115], v[118:119], v[82:83]
	v_pk_mul_f32 v[114:115], v[152:153], v[0:1] op_sel_hi:[1,0]
	v_pk_mul_f32 v[118:119], v[166:167], v[0:1] op_sel_hi:[1,0]
	v_pk_mul_f32 v[114:115], v[120:121], v[114:115]
	s_nop 0
	v_pk_fma_f32 v[84:85], v[116:117], v[114:115], v[84:85]
	v_mov_b64_e32 v[114:115], v[196:197]
	v_mov_b64_e32 v[116:117], v[198:199]
	global_store_dwordx4 v[164:165], v[82:85], off offset:3072
	s_waitcnt lgkmcnt(0)
	v_pk_mul_f32 v[114:115], v[114:115], v[118:119]
	s_waitcnt vmcnt(7)
	v_pk_fma_f32 v[78:79], v[110:111], v[114:115], v[78:79]
	v_pk_mul_f32 v[110:111], v[168:169], v[0:1] op_sel_hi:[1,0]
	v_add_co_u32_e32 v114, vcc, s0, v164
	v_pk_mul_f32 v[110:111], v[116:117], v[110:111]
	v_pk_mul_f32 v[116:117], v[170:171], v[0:1] op_sel_hi:[1,0]
	v_pk_fma_f32 v[80:81], v[112:113], v[110:111], v[80:81]
	v_mov_b64_e32 v[110:111], v[200:201]
	v_mov_b64_e32 v[112:113], v[202:203]
	v_addc_co_u32_e32 v115, vcc, 0, v165, vcc
	s_and_b64 vcc, exec, s[4:5]
	global_store_dwordx4 v[114:115], v[78:81], off
	s_waitcnt lgkmcnt(0)
	v_pk_mul_f32 v[110:111], v[116:117], v[110:111]
	s_waitcnt vmcnt(7)
	v_pk_fma_f32 v[74:75], v[106:107], v[110:111], v[74:75]
	v_pk_mul_f32 v[106:107], v[154:155], v[0:1] op_sel_hi:[1,0]
	v_pk_mul_f32 v[110:111], v[156:157], v[0:1] op_sel_hi:[1,0]
	v_pk_mul_f32 v[106:107], v[106:107], v[112:113]
	s_nop 0
	v_pk_fma_f32 v[76:77], v[108:109], v[106:107], v[76:77]
	v_mov_b64_e32 v[106:107], v[204:205]
	v_mov_b64_e32 v[108:109], v[206:207]
	global_store_dwordx4 v[114:115], v[74:77], off offset:1024
	s_waitcnt lgkmcnt(0)
	v_pk_mul_f32 v[106:107], v[110:111], v[106:107]
	s_waitcnt vmcnt(7)
	v_pk_fma_f32 v[70:71], v[102:103], v[106:107], v[70:71]
	v_pk_mul_f32 v[102:103], v[158:159], v[0:1] op_sel_hi:[1,0]
	v_pk_mul_f32 v[106:107], v[160:161], v[0:1] op_sel_hi:[1,0]
	v_pk_mul_f32 v[102:103], v[102:103], v[108:109]
	s_nop 0
	v_pk_fma_f32 v[72:73], v[104:105], v[102:103], v[72:73]
	v_mov_b64_e32 v[102:103], v[208:209]
	v_mov_b64_e32 v[104:105], v[210:211]
	global_store_dwordx4 v[114:115], v[70:73], off offset:2048
	s_waitcnt lgkmcnt(0)
	v_pk_mul_f32 v[102:103], v[106:107], v[102:103]
	s_waitcnt vmcnt(7)
	v_pk_fma_f32 v[66:67], v[98:99], v[102:103], v[66:67]
	v_pk_mul_f32 v[98:99], v[162:163], v[0:1] op_sel_hi:[1,0]
	s_nop 0
	v_pk_mul_f32 v[98:99], v[98:99], v[104:105]
	s_nop 0
	v_pk_fma_f32 v[68:69], v[100:101], v[98:99], v[68:69]
	global_store_dwordx4 v[114:115], v[66:69], off offset:3072
	s_cbranch_vccnz .LBB0_103
; DI unsigned pack2(float a, float b) { f2_t v = {a, b}; bf2_t r = __builtin_convertvector(v, bf2_t); return __builtin_bit_cast(unsigned, r); }
; DI void rowpass(const Params& p, int l, bool first, int wv, char* smem) {
;     ...
;       if (l < 3) {
;         float s2 = 0.f;
; #pragma unroll
;         for (int i = 0; i < 8; ++i) s2 += hv[i][0] * hv[i][0] + hv[i][1] * hv[i][1] + hv[i][2] * hv[i][2] + hv[i][3] * hv[i][3];
;         s2 = wave_sum(s2);
;         const float r2 = rsqrtf(s2 * (1.f / DM) + EPSV);
;         u16* np = p.nbuf + (size_t)R * DM;
; #pragma unroll
;         for (int i = 0; i < 8; ++i) {
;           const f32x4 grv = *(const f32x4*)(lg_pre + i * 256 + lane * 4);
;           float o[4];
; #pragma unroll
;           for (int e = 0; e < 4; ++e) o[e] = ((hv[i][e] * r2) * grv[e]) * (1.f + scv[i][e]) + shv[i][e];
;           u32x2 pk; pk[0] = pack2(o[0], o[1]); pk[1] = pack2(o[2], o[3]);
;           *(u32x2*)(np + i * 256 + lane * 4) = pk;
;         }
	ds_read_b128 v[180:183], v212 offset:8192
	ds_read_b128 v[184:187], v212 offset:9216
	ds_read_b128 v[188:191], v212 offset:10240
	ds_read_b128 v[192:195], v212 offset:11264
	ds_read_b128 v[196:199], v212 offset:12288
	ds_read_b128 v[200:203], v212 offset:13312
	ds_read_b128 v[204:207], v212 offset:14336
	ds_read_b128 v[208:211], v212 offset:15360
	v_mul_f32_e32 v0, v95, v95
	v_pk_fma_f32 v[98:99], v[94:95], v[94:95], v[0:1] op_sel_hi:[1,1,0]
	v_mul_f32_e32 v0, v97, v97
	v_pk_fma_f32 v[98:99], v[96:97], v[96:97], v[98:99]
	s_ashr_i32 s7, s6, 31
	v_pk_add_f32 v[98:99], v[0:1], v[98:99] op_sel_hi:[0,1]
	v_mul_f32_e32 v0, v91, v91
	v_pk_fma_f32 v[100:101], v[90:91], v[90:91], v[0:1] op_sel_hi:[1,1,0]
	v_mul_f32_e32 v0, v93, v93
	v_pk_fma_f32 v[100:101], v[92:93], v[92:93], v[100:101]
	s_lshl_b64 s[0:1], s[6:7], 12
	v_pk_add_f32 v[100:101], v[0:1], v[100:101] op_sel_hi:[0,1]
	v_mul_f32_e32 v0, v87, v87
	v_pk_add_f32 v[98:99], v[98:99], v[100:101]
	v_pk_fma_f32 v[100:101], v[86:87], v[86:87], v[0:1] op_sel_hi:[1,1,0]
	v_mul_f32_e32 v0, v89, v89
	v_pk_fma_f32 v[100:101], v[88:89], v[88:89], v[100:101]
	s_nop 0
	v_pk_add_f32 v[100:101], v[0:1], v[100:101] op_sel_hi:[0,1]
	v_mul_f32_e32 v0, v83, v83
	v_pk_add_f32 v[98:99], v[100:101], v[98:99]
	v_pk_fma_f32 v[100:101], v[82:83], v[82:83], v[0:1] op_sel_hi:[1,1,0]
	v_mul_f32_e32 v0, v85, v85
	v_pk_fma_f32 v[100:101], v[84:85], v[84:85], v[100:101]
	s_nop 0
	v_pk_add_f32 v[100:101], v[0:1], v[100:101] op_sel_hi:[0,1]
	v_mul_f32_e32 v0, v79, v79
	v_pk_add_f32 v[98:99], v[100:101], v[98:99]
	v_pk_fma_f32 v[100:101], v[78:79], v[78:79], v[0:1] op_sel_hi:[1,1,0]
	v_mul_f32_e32 v0, v81, v81
	v_pk_fma_f32 v[100:101], v[80:81], v[80:81], v[100:101]
	s_nop 0
	v_pk_add_f32 v[100:101], v[0:1], v[100:101] op_sel_hi:[0,1]
	v_mul_f32_e32 v0, v75, v75
	v_pk_add_f32 v[98:99], v[100:101], v[98:99]
	v_pk_fma_f32 v[100:101], v[74:75], v[74:75], v[0:1] op_sel_hi:[1,1,0]
	v_mul_f32_e32 v0, v77, v77
	v_pk_fma_f32 v[100:101], v[76:77], v[76:77], v[100:101]
	s_nop 0
	v_pk_add_f32 v[100:101], v[0:1], v[100:101] op_sel_hi:[0,1]
	v_mul_f32_e32 v0, v71, v71
	v_pk_add_f32 v[98:99], v[100:101], v[98:99]
	v_pk_fma_f32 v[100:101], v[70:71], v[70:71], v[0:1] op_sel_hi:[1,1,0]
	v_mul_f32_e32 v0, v73, v73
	v_pk_fma_f32 v[100:101], v[72:73], v[72:73], v[100:101]
	s_nop 0
	v_pk_add_f32 v[100:101], v[0:1], v[100:101] op_sel_hi:[0,1]
	v_mul_f32_e32 v0, v67, v67
	v_pk_add_f32 v[98:99], v[100:101], v[98:99]
	v_pk_fma_f32 v[100:101], v[66:67], v[66:67], v[0:1] op_sel_hi:[1,1,0]
	v_mul_f32_e32 v0, v69, v69
	v_pk_fma_f32 v[100:101], v[68:69], v[68:69], v[100:101]
	s_nop 0
	v_pk_add_f32 v[100:101], v[0:1], v[100:101] op_sel_hi:[0,1]
	v_pk_add_f32 v[98:99], v[100:101], v[98:99]
	s_waitcnt lgkmcnt(0)
	v_mov_b64_e32 v[100:101], v[180:181]
	v_mov_b64_e32 v[102:103], v[182:183]
	v_mov_b32_e32 v0, v98
	s_nop 1
	v_permlane32_swap_b32_e32 v98, v0
	v_add_f32_e32 v0, v98, v0
	ds_swizzle_b32 v98, v0 offset:swizzle(SWAP,16)
	s_waitcnt lgkmcnt(0)
	v_add_f32_e32 v0, v0, v98
	ds_swizzle_b32 v98, v0 offset:swizzle(SWAP,8)
	s_waitcnt lgkmcnt(0)
	v_add_f32_e32 v0, v0, v98
	ds_swizzle_b32 v98, v0 offset:swizzle(SWAP,4)
	s_waitcnt lgkmcnt(0)
	v_add_f32_e32 v0, v0, v98
	ds_swizzle_b32 v98, v0 offset:swizzle(SWAP,2)
	s_waitcnt lgkmcnt(0)
	v_add_f32_e32 v0, v0, v98
	ds_swizzle_b32 v98, v0 offset:swizzle(SWAP,1)
	s_waitcnt lgkmcnt(0)
	v_add_f32_e32 v0, v0, v98
	v_fmamk_f32 v0, v0, 0x3a000000, v232
	v_cmp_gt_f32_e32 vcc, s2, v0
	v_mul_f32_e32 v98, 0x4b800000, v0
	s_nop 0
	v_cndmask_b32_e32 v0, v0, v98, vcc
	v_rsq_f32_e32 v0, v0
	s_nop 0
	v_mul_f32_e32 v98, 0x45800000, v0
	v_cndmask_b32_e32 v0, v0, v98, vcc
	v_pk_mul_f32 v[94:95], v[94:95], v[0:1] op_sel_hi:[1,0]
	v_pk_mul_f32 v[96:97], v[96:97], v[0:1] op_sel_hi:[1,0]
	v_pk_mul_f32 v[94:95], v[100:101], v[94:95]
	v_pk_add_f32 v[100:101], v[30:31], 1.0 op_sel_hi:[1,0]
	v_pk_mul_f32 v[96:97], v[102:103], v[96:97]
	v_pk_fma_f32 v[94:95], v[100:101], v[94:95], v[2:3]
	v_pk_add_f32 v[100:101], v[32:33], 1.0 op_sel_hi:[1,0]
	v_lshl_add_u64 v[98:99], v[134:135], 0, s[0:1]
	v_pk_fma_f32 v[96:97], v[100:101], v[96:97], v[4:5]
	v_cvt_pk_bf16_f32 v94, v94, v95
	v_cvt_pk_bf16_f32 v95, v96, v97
	global_store_dwordx2 v[98:99], v[94:95], off
	v_mov_b64_e32 v[94:95], v[184:185]
	v_mov_b64_e32 v[96:97], v[186:187]
	v_pk_mul_f32 v[90:91], v[90:91], v[0:1] op_sel_hi:[1,0]
	v_pk_mul_f32 v[92:93], v[92:93], v[0:1] op_sel_hi:[1,0]
	v_pk_mul_f32 v[86:87], v[86:87], v[0:1] op_sel_hi:[1,0]
	v_pk_mul_f32 v[88:89], v[88:89], v[0:1] op_sel_hi:[1,0]
	s_waitcnt lgkmcnt(0)
; DI unsigned pack2(float a, float b) { f2_t v = {a, b}; bf2_t r = __builtin_convertvector(v, bf2_t); return __builtin_bit_cast(unsigned, r); }
; DI void rowpass(const Params& p, int l, bool first, int wv, char* smem) {
;     ...
; #pragma unroll
;         for (int i = 0; i < 8; ++i) {
;           const f32x4 grv = *(const f32x4*)(lg_pre + i * 256 + lane * 4);
;           float o[4];
; #pragma unroll
;           for (int e = 0; e < 4; ++e) o[e] = ((hv[i][e] * r2) * grv[e]) * (1.f + scv[i][e]) + shv[i][e];
;           u32x2 pk; pk[0] = pack2(o[0], o[1]); pk[1] = pack2(o[2], o[3]);
;           *(u32x2*)(np + i * 256 + lane * 4) = pk;
;         }
	v_pk_mul_f32 v[90:91], v[94:95], v[90:91]
	v_pk_add_f32 v[94:95], v[18:19], 1.0 op_sel_hi:[1,0]
	v_pk_mul_f32 v[92:93], v[96:97], v[92:93]
	v_pk_fma_f32 v[90:91], v[94:95], v[90:91], v[6:7]
	v_pk_add_f32 v[94:95], v[20:21], 1.0 op_sel_hi:[1,0]
	v_cvt_pk_bf16_f32 v90, v90, v91
	v_pk_fma_f32 v[92:93], v[94:95], v[92:93], v[8:9]
	v_pk_mul_f32 v[82:83], v[82:83], v[0:1] op_sel_hi:[1,0]
	v_cvt_pk_bf16_f32 v91, v92, v93
	global_store_dwordx2 v[98:99], v[90:91], off offset:512
	v_mov_b64_e32 v[90:91], v[188:189]
	v_mov_b64_e32 v[92:93], v[190:191]
	v_pk_mul_f32 v[84:85], v[84:85], v[0:1] op_sel_hi:[1,0]
	v_pk_mul_f32 v[78:79], v[78:79], v[0:1] op_sel_hi:[1,0]
	v_pk_mul_f32 v[80:81], v[80:81], v[0:1] op_sel_hi:[1,0]
	v_pk_mul_f32 v[74:75], v[74:75], v[0:1] op_sel_hi:[1,0]
	s_waitcnt lgkmcnt(0)
	v_pk_mul_f32 v[86:87], v[90:91], v[86:87]
	v_pk_add_f32 v[90:91], v[22:23], 1.0 op_sel_hi:[1,0]
	v_pk_mul_f32 v[88:89], v[92:93], v[88:89]
	v_pk_fma_f32 v[86:87], v[90:91], v[86:87], v[14:15]
	v_pk_add_f32 v[90:91], v[24:25], 1.0 op_sel_hi:[1,0]
	v_cvt_pk_bf16_f32 v86, v86, v87
	v_pk_fma_f32 v[88:89], v[90:91], v[88:89], v[16:17]
	v_pk_mul_f32 v[76:77], v[76:77], v[0:1] op_sel_hi:[1,0]
	v_cvt_pk_bf16_f32 v87, v88, v89
	global_store_dwordx2 v[98:99], v[86:87], off offset:1024
	v_mov_b64_e32 v[86:87], v[192:193]
	v_mov_b64_e32 v[88:89], v[194:195]
	v_pk_mul_f32 v[70:71], v[70:71], v[0:1] op_sel_hi:[1,0]
	v_pk_mul_f32 v[72:73], v[72:73], v[0:1] op_sel_hi:[1,0]
	v_pk_mul_f32 v[66:67], v[66:67], v[0:1] op_sel_hi:[1,0]
	v_pk_mul_f32 v[68:69], v[68:69], v[0:1] op_sel_hi:[1,0]
	s_waitcnt lgkmcnt(0)
	v_pk_mul_f32 v[82:83], v[86:87], v[82:83]
	v_pk_add_f32 v[86:87], v[26:27], 1.0 op_sel_hi:[1,0]
	v_pk_mul_f32 v[84:85], v[88:89], v[84:85]
	v_pk_fma_f32 v[82:83], v[86:87], v[82:83], v[10:11]
	v_pk_add_f32 v[86:87], v[28:29], 1.0 op_sel_hi:[1,0]
	v_cvt_pk_bf16_f32 v82, v82, v83
	v_pk_fma_f32 v[84:85], v[86:87], v[84:85], v[12:13]
	s_nop 0
	v_cvt_pk_bf16_f32 v83, v84, v85
	global_store_dwordx2 v[98:99], v[82:83], off offset:1536
	v_mov_b64_e32 v[82:83], v[196:197]
	v_mov_b64_e32 v[84:85], v[198:199]
	s_waitcnt lgkmcnt(0)
	v_pk_mul_f32 v[78:79], v[82:83], v[78:79]
	v_pk_add_f32 v[82:83], v[54:55], 1.0 op_sel_hi:[1,0]
	v_pk_mul_f32 v[80:81], v[84:85], v[80:81]
	v_pk_fma_f32 v[78:79], v[82:83], v[78:79], v[34:35]
	v_pk_add_f32 v[82:83], v[56:57], 1.0 op_sel_hi:[1,0]
	v_cvt_pk_bf16_f32 v78, v78, v79
	v_pk_fma_f32 v[80:81], v[82:83], v[80:81], v[36:37]
	s_nop 0
	v_cvt_pk_bf16_f32 v79, v80, v81
	global_store_dwordx2 v[98:99], v[78:79], off offset:2048
	v_mov_b64_e32 v[78:79], v[200:201]
	v_mov_b64_e32 v[80:81], v[202:203]
	s_waitcnt lgkmcnt(0)
	v_pk_mul_f32 v[74:75], v[74:75], v[78:79]
	v_pk_add_f32 v[78:79], v[50:51], 1.0 op_sel_hi:[1,0]
	v_pk_mul_f32 v[76:77], v[76:77], v[80:81]
	v_pk_fma_f32 v[74:75], v[78:79], v[74:75], v[38:39]
	v_pk_add_f32 v[78:79], v[52:53], 1.0 op_sel_hi:[1,0]
	v_cvt_pk_bf16_f32 v74, v74, v75
	v_pk_fma_f32 v[76:77], v[78:79], v[76:77], v[40:41]
	s_nop 0
	v_cvt_pk_bf16_f32 v75, v76, v77
	global_store_dwordx2 v[98:99], v[74:75], off offset:2560
	v_mov_b64_e32 v[74:75], v[204:205]
	v_mov_b64_e32 v[76:77], v[206:207]
	s_waitcnt lgkmcnt(0)
	v_pk_mul_f32 v[70:71], v[70:71], v[74:75]
	v_pk_add_f32 v[74:75], v[62:63], 1.0 op_sel_hi:[1,0]
	v_pk_mul_f32 v[72:73], v[72:73], v[76:77]
	v_pk_fma_f32 v[70:71], v[74:75], v[70:71], v[42:43]
	v_pk_add_f32 v[74:75], v[64:65], 1.0 op_sel_hi:[1,0]
	v_cvt_pk_bf16_f32 v70, v70, v71
	v_pk_fma_f32 v[72:73], v[74:75], v[72:73], v[44:45]
	s_nop 0
	v_cvt_pk_bf16_f32 v71, v72, v73
	global_store_dwordx2 v[98:99], v[70:71], off offset:3072
	v_mov_b64_e32 v[70:71], v[208:209]
	v_mov_b64_e32 v[72:73], v[210:211]
	s_waitcnt lgkmcnt(0)
	v_pk_mul_f32 v[66:67], v[66:67], v[70:71]
	v_pk_add_f32 v[70:71], v[58:59], 1.0 op_sel_hi:[1,0]
	v_pk_mul_f32 v[68:69], v[68:69], v[72:73]
	v_pk_fma_f32 v[66:67], v[70:71], v[66:67], v[46:47]
	v_pk_add_f32 v[70:71], v[60:61], 1.0 op_sel_hi:[1,0]
	v_cvt_pk_bf16_f32 v66, v66, v67
	v_pk_fma_f32 v[68:69], v[70:71], v[68:69], v[48:49]
	s_nop 0
	v_cvt_pk_bf16_f32 v67, v68, v69
	global_store_dwordx2 v[98:99], v[66:67], off offset:3584
	s_branch .LBB0_103

; template <int PM> DI void attn_phase(const Params& p, int l, char* smem, int* s_item, int wv, int cidx) {
;     ...
;   if (tid < 128) sg_s[tid] = p.subln_g[l * 128 + tid];
;   const float li_ = (l == 0) ? 0.2f : (l == 1) ? 0.35550906759096926f : (l == 2) ? 0.47071301834358416f : 0.5560582041556405f;
;   const float lambda_init = __uint_as_float(__builtin_amdgcn_readfirstlane(__float_as_uint(li_)));
;   float lam;
;   {
;     float d1 = p.lq1[l * 64 + lane] * p.lk1[l * 64 + lane];
;     float d2 = p.lq2[l * 64 + lane] * p.lk2[l * 64 + lane];
;     d1 = wave_sum(d1); d2 = wave_sum(d2);
;     lam = expf(d1) - expf(d2) + lambda_init;
;     lam = __uint_as_float(__builtin_amdgcn_readfirstlane(__float_as_uint(lam)));
;   }
;   const int trow = tid >> 4, tch = tid & 15;
;   if (tid == 0) *s_item = atomicAdd(p.counters + cidx, 1);
.LBB0_371:
	s_waitcnt vmcnt(0)
	v_lshl_add_u32 v2, s86, 6, v0
	v_ashrrev_i32_e32 v3, 31, v2
	v_readlane_b32 s16, v253, 5
	v_lshlrev_b64 v[2:3], 2, v[2:3]
	v_readlane_b32 s17, v253, 6
	v_readlane_b32 s18, v253, 7
	v_readlane_b32 s19, v253, 8
	v_lshl_add_u64 v[4:5], s[16:17], 0, v[2:3]
	global_load_dword v6, v[4:5], off
	v_lshl_add_u64 v[4:5], s[18:19], 0, v[2:3]
	global_load_dword v4, v[4:5], off
	v_readlane_b32 s20, v253, 9
	v_readlane_b32 s21, v253, 10
	v_readlane_b32 s22, v253, 11
	v_readlane_b32 s23, v253, 12
	s_lshl_b64 s[0:1], s[86:87], 2
	s_add_u32 s0, s98, s0
	s_addc_u32 s1, s99, s1
	v_writelane_b32 v254, s0, 50
	s_mov_b32 s2, 0x42b17218
	v_mov_b32_e32 v7, 0x7f800000
	v_writelane_b32 v254, s1, 51
	v_cmp_eq_u32_e32 vcc, 0, v238
	v_mov_b32_e32 v14, 1
	s_and_saveexec_b64 s[6:7], vcc
	global_atomic_add v14, v1, v14, s[0:1] sc0
	s_mov_b64 exec, s[6:7]
	s_mov_b32 s0, 0x3fb8aa3b
	s_mov_b32 s1, 0xc2ce8ed0
	v_readlane_b32 s24, v253, 13
	v_readlane_b32 s25, v253, 14
	v_readlane_b32 s26, v253, 15
	v_readlane_b32 s27, v253, 16
	v_readlane_b32 s28, v253, 17
	v_readlane_b32 s29, v253, 18
	v_readlane_b32 s30, v253, 19
	v_readlane_b32 s31, v253, 20
	v_lshl_add_u64 v[10:11], s[20:21], 0, v[2:3]
	v_lshl_add_u64 v[12:13], s[22:23], 0, v[2:3]
	global_load_dword v10, v[10:11], off
	global_load_dword v12, v[12:13], off
	s_waitcnt vmcnt(0)
	v_mul_f32_e32 v6, v6, v4
	v_mov_b32_e32 v3, v6
	s_nop 1
	v_permlane32_swap_b32_e32 v6, v3
	v_add_f32_e32 v3, v6, v3
	v_mul_f32_e32 v2, v10, v12
	ds_swizzle_b32 v4, v3 offset:swizzle(SWAP,16)
	s_waitcnt lgkmcnt(0)
	v_add_f32_e32 v3, v3, v4
	ds_swizzle_b32 v4, v3 offset:swizzle(SWAP,8)
	s_waitcnt lgkmcnt(0)
	v_add_f32_e32 v3, v3, v4
	ds_swizzle_b32 v4, v3 offset:swizzle(SWAP,4)
	s_waitcnt lgkmcnt(0)
	v_add_f32_e32 v3, v3, v4
	ds_swizzle_b32 v4, v3 offset:swizzle(SWAP,2)
	s_waitcnt lgkmcnt(0)
	v_add_f32_e32 v3, v3, v4
	ds_swizzle_b32 v4, v3 offset:swizzle(SWAP,1)
	s_waitcnt lgkmcnt(0)
	v_add_f32_e32 v3, v3, v4
	v_mov_b32_e32 v4, v2
	s_nop 1
	v_permlane32_swap_b32_e32 v2, v4
	v_add_f32_e32 v2, v2, v4
	ds_swizzle_b32 v4, v2 offset:swizzle(SWAP,16)
	v_cmp_ngt_f32_e32 vcc, s1, v3
	s_waitcnt lgkmcnt(0)
	v_add_f32_e32 v2, v2, v4
	ds_swizzle_b32 v4, v2 offset:swizzle(SWAP,8)
	s_waitcnt lgkmcnt(0)
	v_add_f32_e32 v2, v2, v4
	ds_swizzle_b32 v4, v2 offset:swizzle(SWAP,4)
	s_waitcnt lgkmcnt(0)
	v_add_f32_e32 v2, v2, v4
	ds_swizzle_b32 v4, v2 offset:swizzle(SWAP,2)
	s_waitcnt lgkmcnt(0)
	v_add_f32_e32 v2, v2, v4
	ds_swizzle_b32 v4, v2 offset:swizzle(SWAP,1)
	s_waitcnt lgkmcnt(0)
	v_add_f32_e32 v2, v2, v4
	v_mul_f32_e32 v4, 0x3fb8aa3b, v3
	v_fma_f32 v5, v3, s0, -v4
	v_rndne_f32_e32 v6, v4
	v_fmac_f32_e32 v5, 0x32a5705f, v3
	v_sub_f32_e32 v4, v4, v6
	v_add_f32_e32 v4, v4, v5
	v_exp_f32_e32 v4, v4
	v_cvt_i32_f32_e32 v5, v6
	v_ldexp_f32 v4, v4, v5
	v_cndmask_b32_e32 v4, 0, v4, vcc
	v_cmp_nlt_f32_e32 vcc, s2, v3
	s_nop 1
	v_cndmask_b32_e32 v3, v7, v4, vcc
	v_mul_f32_e32 v4, 0x3fb8aa3b, v2
	v_fma_f32 v5, v2, s0, -v4
	v_rndne_f32_e32 v6, v4
	v_fmac_f32_e32 v5, 0x32a5705f, v2
	v_sub_f32_e32 v4, v4, v6
	v_add_f32_e32 v4, v4, v5
	v_exp_f32_e32 v4, v4
	v_cvt_i32_f32_e32 v5, v6
	v_cmp_ngt_f32_e32 vcc, s1, v2
	v_ldexp_f32 v4, v4, v5
	s_nop 0
	v_cndmask_b32_e32 v4, 0, v4, vcc
	v_cmp_nlt_f32_e32 vcc, s2, v2
	v_cmp_eq_u32_e64 s[2:3], 0, v238
	s_nop 0
	v_cndmask_b32_e32 v2, v7, v4, vcc
	v_sub_f32_e32 v2, v3, v2
	v_add_f32_e32 v2, s8, v2
	s_nop 0
	v_readfirstlane_b32 s4, v2
	s_mov_b64 s[0:1], exec
	v_writelane_b32 v254, s2, 52
	s_nop 1
	v_writelane_b32 v254, s3, 53
	s_and_b64 s[2:3], s[0:1], s[2:3]
	s_mov_b64 exec, s[2:3]
	s_cbranch_execz .LBB0_375
	v_mov_b32_e32 v3, 0x24000
	ds_write_b32 v3, v14
